# non-temporal hint on the final RMSNorm phase's last-use bf16 row loads
# baseline (speedup 1.0000x reference)
; __device__ __forceinline__ float bf_lo(unsigned u) { return __uint_as_float(u << 16); }
; __device__ __forceinline__ float bf_hi(unsigned u) { return __uint_as_float(u & 0xffff0000u); }
; __device__ __forceinline__ void final_rows(const bf16_t* hb, const float* g, float* outf, int gw, int NGW, int lane, int m_lo, int m_hi) {
;     ...
;     for (int m0 = m_lo + gw; m0 < m_hi; m0 += 4 * NGW) {
;         u32x2 w[4][4];
; #pragma unroll
;         for (int r = 0; r < 4; ++r) { const int m = m0 + r * NGW < m_hi ? m0 + r * NGW : m_hi - 1; const u32x2* xr = (const u32x2*)(hb + (size_t)m * D) + lane;
; #pragma unroll
;             for (int j = 0; j < 4; ++j) w[r][j] = xr[64 * j]; }
; #pragma unroll
;         for (int r = 0; r < 4; ++r) { const int m = m0 + r * NGW; f32x4 v[4]; float s = 0.f;
; #pragma unroll
;             for (int j = 0; j < 4; ++j) { v[j] = (f32x4){bf_lo(w[r][j].x), bf_hi(w[r][j].x), bf_lo(w[r][j].y), bf_hi(w[r][j].y)}; s += (v[j].x * v[j].x + v[j].y * v[j].y) + (v[j].z * v[j].z + v[j].w * v[j].w); }
;             const float rstd = 1.0f / sqrtf(wave_sum(s) * (1.0f / D) + EPS);
.LBB0_17:
	s_min_i32 s10, s8, s7
	s_ashr_i32 s11, s10, 31
	s_lshl_b64 s[10:11], s[10:11], 11
	v_lshl_add_u64 v[20:21], v[16:17], 0, s[10:11]
	s_add_i32 s10, s8, s1
	s_min_i32 s12, s10, s7
	global_load_dwordx2 v[38:39], v[20:21], off nt
	global_load_dwordx2 v[40:41], v[20:21], off offset:512 nt
	global_load_dwordx2 v[42:43], v[20:21], off offset:1024 nt
	global_load_dwordx2 v[58:59], v[20:21], off offset:1536 nt
	s_ashr_i32 s13, s12, 31
	s_lshl_b64 s[12:13], s[12:13], 11
	v_lshl_add_u64 v[20:21], v[16:17], 0, s[12:13]
	global_load_dwordx2 v[66:67], v[20:21], off nt
	global_load_dwordx2 v[62:63], v[20:21], off offset:512 nt
	global_load_dwordx2 v[60:61], v[20:21], off offset:1024 nt
	global_load_dwordx2 v[64:65], v[20:21], off offset:1536 nt
	s_mul_i32 s11, s1, 3
	s_add_i32 s14, s16, s8
	s_add_i32 s12, s11, s8
	s_ashr_i32 s9, s8, 31
	s_min_i32 s18, s14, s7
	s_min_i32 s20, s12, s7
	s_lshl_b64 s[8:9], s[8:9], 12
	s_ashr_i32 s19, s18, 31
	s_ashr_i32 s21, s20, 31
	s_waitcnt lgkmcnt(0)
	v_lshl_add_u64 v[36:37], v[18:19], 0, s[8:9]
	s_lshl_b64 s[8:9], s[18:19], 11
	s_lshl_b64 s[18:19], s[20:21], 11
	v_lshl_add_u64 v[20:21], v[16:17], 0, s[8:9]
	v_lshl_add_u64 v[44:45], v[16:17], 0, s[18:19]
	global_load_dwordx2 v[34:35], v[20:21], off nt
	global_load_dwordx2 v[32:33], v[20:21], off offset:512 nt
	global_load_dwordx2 v[30:31], v[20:21], off offset:1024 nt
	global_load_dwordx2 v[28:29], v[20:21], off offset:1536 nt
	global_load_dwordx2 v[26:27], v[44:45], off nt
	global_load_dwordx2 v[24:25], v[44:45], off offset:512 nt
	global_load_dwordx2 v[22:23], v[44:45], off offset:1024 nt
	s_nop 0
	global_load_dwordx2 v[20:21], v[44:45], off offset:1536 nt
	s_mov_b32 s8, 0xf800000
	s_cmp_ge_i32 s10, s0
	s_waitcnt vmcnt(15)
	v_and_b32_e32 v77, 0xffff0000, v38
	v_and_b32_e32 v57, 0xffff0000, v39
	v_lshlrev_b32_e32 v76, 16, v38
	v_lshlrev_b32_e32 v56, 16, v39
	s_waitcnt vmcnt(14)
	v_and_b32_e32 v53, 0xffff0000, v41
	v_and_b32_e32 v52, 0xffff0000, v40
	s_waitcnt vmcnt(13)
	v_and_b32_e32 v49, 0xffff0000, v42
	s_waitcnt vmcnt(12)
	v_lshlrev_b32_e32 v47, 16, v58
	v_and_b32_e32 v45, 0xffff0000, v58
	v_mul_f32_e32 v44, v57, v57
	v_mul_f32_e32 v46, v77, v77
	v_lshlrev_b32_e32 v55, 16, v41
	v_lshlrev_b32_e32 v54, 16, v40
	v_lshlrev_b32_e32 v48, 16, v42
	v_lshlrev_b32_e32 v50, 16, v43
	v_and_b32_e32 v51, 0xffff0000, v43
	v_lshlrev_b32_e32 v42, 16, v59
	v_and_b32_e32 v43, 0xffff0000, v59
	v_pk_mul_f32 v[58:59], v[52:53], v[52:53]
	v_mov_b32_e32 v69, v47
	v_mul_f32_e32 v68, v49, v49
	s_waitcnt vmcnt(11)
	v_lshlrev_b32_e32 v40, 16, v66
	v_and_b32_e32 v41, 0xffff0000, v66
	v_lshlrev_b32_e32 v38, 16, v67
	v_and_b32_e32 v39, 0xffff0000, v67
	v_pk_fma_f32 v[66:67], v[56:57], v[56:57], v[44:45] op_sel_hi:[1,1,0]
	v_pk_fma_f32 v[80:81], v[76:77], v[76:77], v[46:47] op_sel_hi:[1,1,0]
	v_mul_f32_e32 v78, v51, v51
	v_pk_fma_f32 v[58:59], v[54:55], v[54:55], v[58:59]
	v_pk_fma_f32 v[82:83], v[48:49], v[48:49], v[68:69] op_sel_hi:[1,1,0]
	v_mov_b32_e32 v46, v80
	v_mov_b32_e32 v68, v66
	v_mul_f32_e32 v84, v45, v45
	v_mul_f32_e32 v85, v42, v42
	v_mul_f32_e32 v86, v43, v43
	v_pk_fma_f32 v[78:79], v[50:51], v[50:51], v[78:79] op_sel_hi:[1,1,0]
	v_pk_add_f32 v[66:67], v[80:81], v[66:67]
	v_pk_add_f32 v[58:59], v[58:59], v[58:59] op_sel:[0,1] op_sel_hi:[1,0]
	v_pk_mul_f32 v[68:69], v[46:47], v[68:69]
	v_mov_b32_e32 v83, v85
	v_mov_b32_e32 v79, v86
	v_mov_b32_e32 v59, v84
	v_mov_b32_e32 v67, v69
	v_pk_add_f32 v[78:79], v[82:83], v[78:79]
	v_pk_add_f32 v[58:59], v[66:67], v[58:59]
	s_waitcnt vmcnt(9)
	v_lshlrev_b32_e32 v66, 16, v60
	v_pk_add_f32 v[58:59], v[58:59], v[78:79]
	v_mul_f32_e32 v78, v41, v41
	v_add_f32_e32 v44, v58, v59
	ds_bpermute_b32 v46, v70, v44
	v_lshlrev_b32_e32 v58, 16, v62
	v_and_b32_e32 v59, 0xffff0000, v62
	v_lshlrev_b32_e32 v62, 16, v63
	v_and_b32_e32 v63, 0xffff0000, v63
	s_waitcnt lgkmcnt(0)
	v_add_f32_e32 v44, v44, v46
	ds_bpermute_b32 v46, v71, v44
	v_mul_f32_e32 v79, v39, v39
	v_mul_f32_e32 v80, v59, v59
	v_mul_f32_e32 v81, v63, v63
	v_and_b32_e32 v67, 0xffff0000, v60
	s_waitcnt lgkmcnt(0)
	v_add_f32_e32 v44, v44, v46
	ds_bpermute_b32 v46, v72, v44
	v_lshlrev_b32_e32 v60, 16, v61
	v_and_b32_e32 v61, 0xffff0000, v61
	v_fmac_f32_e32 v78, v40, v40
	v_fmac_f32_e32 v79, v38, v38
	s_waitcnt lgkmcnt(0)
	v_add_f32_e32 v44, v44, v46
	ds_bpermute_b32 v46, v73, v44
	v_fmac_f32_e32 v80, v58, v58
	v_fmac_f32_e32 v81, v62, v62
	v_mul_f32_e32 v82, v67, v67
	v_mul_f32_e32 v83, v61, v61
	s_waitcnt lgkmcnt(0)
	v_add_f32_e32 v44, v44, v46
	ds_bpermute_b32 v46, v74, v44
	v_add_f32_e32 v78, v78, v79
	v_add_f32_e32 v79, v80, v81
	v_fmac_f32_e32 v82, v66, v66
	v_fmac_f32_e32 v83, v60, v60
	s_waitcnt lgkmcnt(0)
	v_add_f32_e32 v44, v44, v46
	ds_bpermute_b32 v46, v75, v44
	v_add_f32_e32 v78, v78, v79
	v_add_f32_e32 v80, v82, v83
	v_add_f32_e32 v78, v78, v80
	s_waitcnt vmcnt(8)
	v_lshlrev_b32_e32 v68, 16, v64
	s_waitcnt lgkmcnt(0)
; __device__ __forceinline__ float bf_lo(unsigned u) { return __uint_as_float(u << 16); }
; __device__ __forceinline__ float bf_hi(unsigned u) { return __uint_as_float(u & 0xffff0000u); }
; __device__ __forceinline__ void final_rows(const bf16_t* hb, const float* g, float* outf, int gw, int NGW, int lane, int m_lo, int m_hi) {
;     ...
;         for (int r = 0; r < 4; ++r) { const int m = m0 + r * NGW; f32x4 v[4]; float s = 0.f;
; #pragma unroll
;             for (int j = 0; j < 4; ++j) { v[j] = (f32x4){bf_lo(w[r][j].x), bf_hi(w[r][j].x), bf_lo(w[r][j].y), bf_hi(w[r][j].y)}; s += (v[j].x * v[j].x + v[j].y * v[j].y) + (v[j].z * v[j].z + v[j].w * v[j].w); }
;             const float rstd = 1.0f / sqrtf(wave_sum(s) * (1.0f / D) + EPS);
;             if (m < m_hi) { f32x4* o = (f32x4*)(outf + (size_t)m * D) + lane;
; #pragma unroll
;                 for (int j = 0; j < 4; ++j) o[64 * j] = v[j] * rstd * gv[j]; } }
	v_add_f32_e32 v44, v44, v46
	v_fmamk_f32 v44, v44, 0x3a800000, v223
	v_mul_f32_e32 v46, 0x4f800000, v44
	v_cmp_gt_f32_e32 vcc, s8, v44
	v_and_b32_e32 v69, 0xffff0000, v64
	v_lshlrev_b32_e32 v64, 16, v65
	v_cndmask_b32_e32 v44, v44, v46, vcc
	v_sqrt_f32_e32 v46, v44
	v_and_b32_e32 v65, 0xffff0000, v65
	v_add_u32_e32 v79, -1, v46
	v_add_u32_e32 v81, 1, v46
	v_fma_f32 v82, -v79, v46, v44
	v_fma_f32 v83, -v81, v46, v44
	v_cmp_ge_f32_e64 s[8:9], 0, v82
	s_nop 1
	v_cndmask_b32_e64 v46, v46, v79, s[8:9]
	v_cmp_lt_f32_e64 s[8:9], 0, v83
	s_nop 1
	v_cndmask_b32_e64 v46, v46, v81, s[8:9]
	v_mul_f32_e32 v79, 0x37800000, v46
	v_cndmask_b32_e32 v46, v46, v79, vcc
	v_cmp_class_f32_e32 vcc, v44, v224
	s_nop 1
	v_cndmask_b32_e32 v44, v46, v44, vcc
	v_div_scale_f32 v46, s[8:9], v44, v44, 1.0
	v_rcp_f32_e32 v79, v46
	v_div_scale_f32 v80, vcc, 1.0, v44, 1.0
	v_fma_f32 v81, -v46, v79, 1.0
	v_fmac_f32_e32 v79, v81, v79
	v_mul_f32_e32 v81, v80, v79
	v_fma_f32 v82, -v46, v81, v80
	v_fmac_f32_e32 v81, v82, v79
	v_fma_f32 v46, -v46, v81, v80
	v_div_fmas_f32 v46, v46, v79, v81
	v_div_fixup_f32 v46, v46, v44, 1.0
	v_mul_f32_e32 v44, v69, v69
	v_mul_f32_e32 v79, v65, v65
	v_fmac_f32_e32 v44, v68, v68
	v_fmac_f32_e32 v79, v64, v64
	v_add_f32_e32 v44, v44, v79
	v_add_f32_e32 v44, v78, v44
	ds_bpermute_b32 v80, v70, v44
	v_pk_mul_f32 v[76:77], v[46:47], v[76:77] op_sel_hi:[0,1]
	v_pk_mul_f32 v[56:57], v[46:47], v[56:57] op_sel_hi:[0,1]
	v_pk_mul_f32 v[78:79], v[2:3], v[56:57]
	v_pk_mul_f32 v[76:77], v[0:1], v[76:77]
	s_waitcnt lgkmcnt(0)
	v_add_f32_e32 v44, v44, v80
	global_store_dwordx4 v[36:37], v[76:79], off
	ds_bpermute_b32 v76, v71, v44
	v_mov_b32_e32 v56, v54
	v_mov_b32_e32 v57, v52
	v_mov_b32_e32 v52, v55
	v_pk_mul_f32 v[56:57], v[46:47], v[56:57] op_sel_hi:[0,1]
	s_waitcnt lgkmcnt(0)
	v_add_f32_e32 v44, v44, v76
	ds_bpermute_b32 v76, v72, v44
	v_pk_mul_f32 v[52:53], v[46:47], v[52:53] op_sel_hi:[0,1]
	v_pk_mul_f32 v[54:55], v[6:7], v[52:53]
	v_pk_mul_f32 v[52:53], v[4:5], v[56:57]
	global_store_dwordx4 v[36:37], v[52:55], off offset:1024
	s_waitcnt lgkmcnt(0)
	v_add_f32_e32 v44, v44, v76
	ds_bpermute_b32 v52, v73, v44
	v_pk_mul_f32 v[48:49], v[46:47], v[48:49] op_sel_hi:[0,1]
	v_pk_mul_f32 v[50:51], v[46:47], v[50:51] op_sel_hi:[0,1]
	v_pk_mul_f32 v[50:51], v[10:11], v[50:51]
	v_pk_mul_f32 v[48:49], v[8:9], v[48:49]
	s_waitcnt lgkmcnt(0)
	v_add_f32_e32 v52, v44, v52
	ds_bpermute_b32 v53, v74, v52
	v_mov_b32_e32 v44, v47
	v_pk_mul_f32 v[44:45], v[44:45], v[46:47] op_sel_hi:[1,0]
	v_pk_mul_f32 v[46:47], v[42:43], v[46:47] op_sel_hi:[1,0]
	v_pk_mul_f32 v[44:45], v[12:13], v[44:45]
	s_waitcnt lgkmcnt(0)
	v_add_f32_e32 v42, v52, v53
	ds_bpermute_b32 v43, v75, v42
	v_pk_mul_f32 v[46:47], v[14:15], v[46:47]
	global_store_dwordx4 v[36:37], v[48:51], off offset:2048
	global_store_dwordx4 v[36:37], v[44:47], off offset:3072
	s_cbranch_scc1 .LBB0_19
	s_waitcnt lgkmcnt(0)
	v_add_f32_e32 v36, v42, v43
	v_fmamk_f32 v36, v36, 0x3a800000, v223
	s_mov_b32 s8, 0xf800000
	v_mul_f32_e32 v37, 0x4f800000, v36
	v_cmp_gt_f32_e32 vcc, s8, v36
	s_ashr_i32 s11, s10, 31
	s_nop 0
	v_cndmask_b32_e32 v36, v36, v37, vcc
	v_sqrt_f32_e32 v37, v36
	s_nop 0
	v_add_u32_e32 v42, -1, v37
	v_fma_f32 v44, -v42, v37, v36
	v_add_u32_e32 v43, 1, v37
	v_cmp_ge_f32_e64 s[8:9], 0, v44
	s_nop 1
	v_cndmask_b32_e64 v42, v37, v42, s[8:9]
	v_fma_f32 v37, -v43, v37, v36
	v_cmp_lt_f32_e64 s[8:9], 0, v37
	s_nop 1
	v_cndmask_b32_e64 v37, v42, v43, s[8:9]
	v_mul_f32_e32 v42, 0x37800000, v37
	v_cndmask_b32_e32 v37, v37, v42, vcc
	v_cmp_class_f32_e32 vcc, v36, v224
	s_nop 1
	v_cndmask_b32_e32 v36, v37, v36, vcc
	v_div_scale_f32 v37, s[8:9], v36, v36, 1.0
	v_rcp_f32_e32 v42, v37
	s_lshl_b64 s[8:9], s[10:11], 12
	v_fma_f32 v43, -v37, v42, 1.0
	v_fmac_f32_e32 v42, v43, v42
	v_div_scale_f32 v43, vcc, 1.0, v36, 1.0
	v_mul_f32_e32 v44, v43, v42
	v_fma_f32 v45, -v37, v44, v43
	v_fmac_f32_e32 v44, v45, v42
	v_fma_f32 v37, -v37, v44, v43
	v_div_fmas_f32 v37, v37, v42, v44
	v_div_fixup_f32 v42, v37, v36, 1.0
	v_pk_mul_f32 v[36:37], v[40:41], v[42:43] op_sel_hi:[1,0]
	v_pk_mul_f32 v[38:39], v[38:39], v[42:43] op_sel_hi:[1,0]
	v_lshl_add_u64 v[44:45], v[18:19], 0, s[8:9]
	v_pk_mul_f32 v[38:39], v[2:3], v[38:39]
	v_pk_mul_f32 v[36:37], v[0:1], v[36:37]
	global_store_dwordx4 v[44:45], v[36:39], off
	s_nop 1
	v_pk_mul_f32 v[36:37], v[58:59], v[42:43] op_sel_hi:[1,0]
	v_pk_mul_f32 v[38:39], v[62:63], v[42:43] op_sel_hi:[1,0]
	v_pk_mul_f32 v[36:37], v[4:5], v[36:37]
	v_pk_mul_f32 v[38:39], v[6:7], v[38:39]
	global_store_dwordx4 v[44:45], v[36:39], off offset:1024
	s_nop 1
	v_pk_mul_f32 v[36:37], v[66:67], v[42:43] op_sel_hi:[1,0]
	v_pk_mul_f32 v[38:39], v[60:61], v[42:43] op_sel_hi:[1,0]
	v_pk_mul_f32 v[36:37], v[8:9], v[36:37]
	v_pk_mul_f32 v[38:39], v[10:11], v[38:39]
	global_store_dwordx4 v[44:45], v[36:39], off offset:2048
	s_nop 1
	v_pk_mul_f32 v[36:37], v[68:69], v[42:43] op_sel_hi:[1,0]
	v_pk_mul_f32 v[38:39], v[64:65], v[42:43] op_sel_hi:[1,0]
	v_pk_mul_f32 v[36:37], v[12:13], v[36:37]
	v_pk_mul_f32 v[38:39], v[14:15], v[38:39]
	global_store_dwordx4 v[44:45], v[36:39], off offset:3072
